# gates GEMM: closing workgroup barrier moved below the tile-address code and the four gate-weight B-tile stage loads (weights converted in the prologue, 3 grid barriers earlier); rest as previous best
# baseline (speedup 1.0000x reference)
;     __device__ __forceinline__ void init(AccT& acc, const Unit& u, int wr, int wc, int fr, int fq) const { acc_from_xb(acc, xb, u, wr, wc, fr, fq); }
;     __device__ __forceinline__ void init(AccT& acc, const Unit& u, int wr, int wc, int fr, int fq) const { acc_from_xb(acc, xb, u, wr, wc, fr, fq); }
; template <class Epi, class Sched, bool ALIGN_EPI = false, bool SP2 = false>
; __device__ __forceinline__ void gemm_phase(PG8_LAS unsigned char* lds, const Gemm g, const Sched& S, const Epi& E, const int wid) {
;     ...
;     if (!S.next(0, cur)) return;
; __global__ void __launch_bounds__(NTHREADS, 2) fwd_megakernel(Params p) {
;     ...
;     {   pg8::Gemm g{R2, (const bf16_t*)(ws + WS_WG), MTOK, 2048, 256, DM, 256, 1}; pg8::StaticOrder S; S.init(MTOK, 2048, G, bx);
;         pg8::EpiGates E{R2, p.in[7], p.in[9], (const float*)(ws + WS_C8), AU};
;         pg8::gemm_phase<pg8::EpiGates, pg8::StaticOrder, true, true>(lds, g, S, E, wave);
.LBB0_248:
	s_or_b64 exec, exec, s[4:5]
	s_add_u32 s12, s90, 0x9a00000
	s_addc_u32 s13, s91, 0
	s_add_u32 s18, s90, 0xba00000
	s_addc_u32 s19, s91, 0
	s_mov_b32 s54, 4
	s_andn2_b64 vcc, exec, s[8:9]
	v_mbcnt_lo_u32_b32 v8, -1, 0
	v_mbcnt_hi_u32_b32 v8, -1, v8
	s_cbranch_vccnz .LBB0_250
	s_ashr_i32 s21, s42, 31
	s_mov_b32 s20, s42
	s_mov_b32 s3, 0
	s_cbranch_execz .LBB0_251
	s_barrier
	s_branch .LBB0_278

;     __host__ __device__ bool next(int i, Unit& u) const {
;         const long L = (long)i * G + c; if (L >= nwg) return false;
;         int wgid = (int)L; { const int q = nwg / NXCD, r = nwg % NXCD, xcd = wgid % NXCD, off = wgid / NXCD; wgid = (xcd < r ? xcd * (q + 1) : r * (q + 1) + (xcd - r) * q) + off; }
; template <class Epi, class Sched, bool ALIGN_EPI = false, bool SP2 = false>
; __device__ __forceinline__ void gemm_phase(PG8_LAS unsigned char* lds, const Gemm g, const Sched& S, const Epi& E, const int wid) {
;     const int lane = fresh_lane(), tid = wid * 64 + lane, wr = wid >> 2, wc = wid & 3, fr = lane & 15, fq = lane >> 4;
;     int nt = g.K / BK; asm volatile("" : "+s"(nt));
;     unsigned voffA[2], voffB[2];
; #pragma unroll
;     for (int i = 0; i < 2; ++i) { int R, C; stage_rc(tid * 16 + i * 8192, R, C); const int Rb = Epi::PERM ? ((R & ~31) + perm32(R & 31)) : R;
;         voffA[i] = (unsigned)(R * g.lda + C) * 2u; voffB[i] = (unsigned)(Rb * g.ldb + C) * 2u; }
;     const size_t kstep = (size_t)(BK * 2);
;     const size_t hstepA = (size_t)HALF * g.lda * 2, hstepB = (size_t)HALF * g.ldb * 2;
;     const size_t tstepA = 2 * hstepA, tstepB = 2 * hstepB;
;     const unsigned ldsw = (unsigned)wid * 1024u;
;     const int aoff = lds_byte(wr * 64 + fr, fq * 8), boff = lds_byte(wc * 32 + fr, fq * 8);
;     ...
;     Unit cur, nxt; int ui = 0;
;     if (!S.next(0, cur)) return;
;     f32x4 acc[2][2][4][2];
;     if constexpr (Epi::ACC_INIT) E.init(acc, cur, wr, wc, fr, fq);
;     else {
; #pragma unroll
;     for (int a = 0; a < 2; ++a)
; #pragma unroll
;         for (int b = 0; b < 2; ++b)
; #pragma unroll
;             for (int m = 0; m < 4; ++m)
; #pragma unroll
;                 for (int n = 0; n < 2; ++n) acc[a][b][m][n] = (f32x4){0.f, 0.f, 0.f, 0.f};
;     }
;     bf16x8 At[4][2], B0[2][2], B1[2][2];
;     const char* cA = cur.pn >= g.swap_pn ? (const char*)g.A2 + (size_t)(cur.pn - g.swap_pn) * tstepA : (const char*)g.A + (size_t)cur.pm * tstepA + (g.bd ? (size_t)(cur.pn >> 1) * 512 : 0);
;     const char* cB = cur.pn >= g.swap_pn ? (const char*)g.B2 + (size_t)cur.pm * tstepB : (const char*)g.Bt + (size_t)cur.pn * tstepB;
;     S.a_ready(cur);
;     if constexpr (SP2) {
;         PG8_STAGE(PG8_SB(0, 0), cB, voffB); PG8_STAGE(PG8_SB(0, 1), cB + hstepB, voffB); PG8_STAGE(PG8_SA(0, 0), cA, voffA); PG8_STAGE(PG8_SA(0, 1), cA + hstepA, voffA);
.LBB0_255:
	v_lshl_add_u32 v0, v8, 4, s0
	v_ashrrev_i32_e32 v1, 31, v0
	v_lshrrev_b32_e32 v1, 22, v1
	v_add_u32_e32 v1, v0, v1
	v_ashrrev_i32_e32 v9, 10, v1
	v_mul_i32_i24_e32 v1, 0x400, v9
	v_sub_u32_e32 v1, v0, v1
	v_lshrrev_b32_e32 v2, 4, v1
	v_bitop3_b32 v1, v2, v1, 32 bitop3:0x6c
	v_ashrrev_i32_e32 v3, 31, v1
	v_lshrrev_b32_e32 v3, 26, v3
	v_add_u32_e32 v3, v1, v3
	v_lshlrev_b32_e32 v2, 3, v9
	v_ashrrev_i32_e32 v10, 6, v3
	v_and_b32_e32 v3, 0xc0, v3
	v_and_b32_e32 v2, -16, v2
	v_sub_u32_e32 v1, v1, v3
	v_mov_b32_e32 v3, 1
	v_add_u32_e32 v2, v10, v2
	v_ashrrev_i16_sdwa v1, v3, sext(v1) dst_sel:DWORD dst_unused:UNUSED_PAD src0_sel:DWORD src1_sel:BYTE_0
	v_lshlrev_b32_e32 v4, 5, v9
	v_bfe_i32 v11, v1, 0, 16
	v_lshlrev_b32_e32 v1, 1, v2
	v_lshrrev_b32_e32 v5, 2, v2
	v_and_b32_e32 v6, 3, v10
	s_mov_b32 s5, 0x7fffe0
	v_and_b32_e32 v4, 32, v4
	v_and_b32_e32 v1, 24, v1
	v_and_b32_e32 v5, 4, v5
	v_and_or_b32 v6, v2, s5, v6
	v_or3_b32 v1, v6, v5, v1
	v_add_lshl_u32 v4, v4, v11, 1
	v_add_u32_e32 v0, 0x2000, v0
	v_lshl_add_u32 v154, v1, 9, v4
	v_ashrrev_i32_e32 v1, 31, v0
	v_lshrrev_b32_e32 v1, 22, v1
	v_add_u32_e32 v1, v0, v1
	v_ashrrev_i32_e32 v12, 10, v1
	v_mul_i32_i24_e32 v1, 0x400, v12
	v_sub_u32_e32 v0, v0, v1
	v_lshrrev_b32_e32 v1, 4, v0
	v_bitop3_b32 v0, v1, v0, 32 bitop3:0x6c
	v_lshl_add_u32 v152, v2, 11, v4
	v_ashrrev_i32_e32 v2, 31, v0
	v_lshrrev_b32_e32 v2, 26, v2
	v_add_u32_e32 v2, v0, v2
	v_ashrrev_i32_e32 v13, 6, v2
	v_and_b32_e32 v2, 0xffc0, v2
	v_sub_u32_e32 v0, v0, v2
	v_lshrrev_b16_e32 v2, 7, v0
	s_ashr_i32 s4, s7, 3
	v_lshlrev_b32_e32 v1, 3, v12
	v_and_b32_e32 v2, 1, v2
	s_add_u32 s55, s90, 0x500000
	v_and_b32_e32 v1, -16, v1
	v_add_u16_e32 v0, v0, v2
	s_addc_u32 s56, s91, 0
	v_add_u32_e32 v1, v13, v1
	v_ashrrev_i16_sdwa v0, v3, sext(v0) dst_sel:DWORD dst_unused:UNUSED_PAD src0_sel:DWORD src1_sel:BYTE_0
	v_and_b32_e32 v3, 3, v13
	s_add_i32 s4, s6, s4
	v_and_or_b32 v3, v1, s5, v3
	s_ashr_i32 s5, s4, 31
	s_lshr_b32 s5, s5, 26
	s_add_i32 s5, s4, s5
	s_ashr_i32 s6, s5, 6
	s_andn2_b32 s5, s5, 63
	s_sub_i32 s5, s4, s5
	s_bfe_i32 s4, s5, 0x80000
	s_bfe_u32 s4, s4, 0x3000c
	s_add_i32 s8, s5, s4
	s_bfe_i32 s4, s8, 0x80000
	s_and_b32 s8, s8, 0xf8
	s_sub_i32 s5, s5, s8
	s_lshl_b32 s7, s6, 3
	s_sext_i32_i8 s5, s5
	s_add_i32 s40, s7, s5
	s_sext_i32_i16 s4, s4
	s_ashr_i32 s41, s40, 31
	s_lshr_b32 s6, s4, 3
	s_lshl_b64 s[8:9], s[40:41], 19
	s_add_u32 s5, s12, s8
	s_addc_u32 s7, s13, s9
	s_ashr_i32 s8, s4, 4
	s_ashr_i32 s9, s8, 31
	s_lshl_b64 s[8:9], s[8:9], 9
	s_add_u32 s44, s5, s8
	s_addc_u32 s45, s7, s9
	s_bfe_i64 s[6:7], s[6:7], 0x100000
	s_lshl_b64 s[6:7], s[6:7], 17
	s_add_u32 s46, s55, s6
	v_lshlrev_b32_e32 v4, 5, v12
	v_bfe_i32 v14, v0, 0, 16
	v_lshlrev_b32_e32 v0, 1, v1
	v_lshrrev_b32_e32 v2, 2, v1
	s_addc_u32 s47, s56, s7
	s_add_i32 s41, s0, 0
	v_and_b32_e32 v4, 32, v4
	v_and_b32_e32 v0, 24, v0
	v_and_b32_e32 v2, 4, v2
	s_add_i32 m0, s41, 0x10000
	v_or3_b32 v0, v3, v2, v0
	v_add_lshl_u32 v2, v4, v14, 1
	global_load_lds_dwordx4 v154, s[46:47]
	s_add_i32 m0, s41, 0x12000
	v_lshl_add_u32 v158, v0, 9, v2
	s_add_u32 s6, s46, 0x10000
	global_load_lds_dwordx4 v158, s[46:47]
	s_addc_u32 s7, s47, 0
	s_add_i32 m0, s41, 0x14000
	s_add_i32 s57, s41, 0x2000
	global_load_lds_dwordx4 v154, s[6:7]
	s_add_i32 m0, s41, 0x16000
	v_lshl_add_u32 v156, v1, 11, v2
	global_load_lds_dwordx4 v158, s[6:7]
	s_barrier
	s_mov_b32 m0, s41
	s_add_u32 s6, s44, 0x40000
	global_load_lds_dwordx4 v152, s[44:45]
	s_mov_b32 m0, s57
	s_addc_u32 s7, s45, 0
	s_add_i32 s58, s41, 0x4000
	global_load_lds_dwordx4 v156, s[44:45]
	s_mov_b32 m0, s58
	s_add_i32 s59, s41, 0x6000
	global_load_lds_dwordx4 v152, s[6:7]
	s_mov_b32 m0, s59
	v_mov_b32_e32 v161, 0
	global_load_lds_dwordx4 v156, s[6:7]
	v_mov_b32_e32 v155, v161
	v_mov_b32_e32 v159, v161
	v_mov_b32_e32 v153, v161
	v_mov_b32_e32 v157, v161
	s_cmp_eq_u32 s1, 1
	s_mov_b32 s60, 0
	v_lshl_add_u64 v[6:7], s[46:47], 0, v[154:155]
	v_lshl_add_u64 v[4:5], s[46:47], 0, v[158:159]
	v_lshl_add_u64 v[0:1], s[44:45], 0, v[152:153]
	s_cselect_b64 s[8:9], -1, 0
	s_cmp_lg_u32 s1, 1
	v_lshl_add_u64 v[2:3], s[44:45], 0, v[156:157]
	s_cbranch_scc1 .LBB0_257
	s_barrier
